# speedup vs baseline: 1.0504x; 1.0068x over previous
; __device__ __forceinline__ unsigned cvt_pk_bf16(float lo, float hi) { return __builtin_bit_cast(unsigned, __builtin_amdgcn_cvt_pkrtz(lo, hi)); }
; __device__ __forceinline__ void ssm_proj_load(SsmProj& P, const float* SSB, int g, int fr, int fq) {
; #pragma unroll
;     for (int nt = 0; nt < 8; ++nt) { const int cg = 16 * nt + fr, p = cg >> 1, c = cg & 1; u32x4 w = {0u, 0u, 0u, 0u};
;         if (fq < 2) { const float* s = SSB + ((size_t)g * 64 + p) * 32 + c * 16 + 8 * fq; const f32x4 a = *(const f32x4*)s, b = *(const f32x4*)(s + 4);
;             w = (u32x4){cvt_pk_bf16(a[0], a[1]), cvt_pk_bf16(a[2], a[3]), cvt_pk_bf16(b[0], b[1]), cvt_pk_bf16(b[2], b[3])}; }
;         P.bf[nt] = __builtin_bit_cast(bf16x8, w); }
; }
; __device__ __forceinline__ void phase_ssm2(int wid_s, unsigned char* shm, const float* US, const float* SSA, const float* SSB, const float* FIN, const float* c_re, const float* c_im, const float* dvec, bf16_t* YG) {
;     ...
;     for (int item = blockIdx.x; item < BATCH * 8 * (NCH / 2); item += gridDim.x) {
;         const int cp = (item >= 256) ? 15 - (item & 15) : (item & 15), gq = (item >> 4) & 7, b = item >> 7, g = gq * 4 + gl, ch = cp * 2 + (wid >> 2);
;         SsmProj P; ssm_proj_load(P, SSB, g, fr, fq);
.LBB0_472:
	s_lshr_b32 s6, s10, 2
	v_and_or_b32 v3, s6, 28, v81
	v_lshl_or_b32 v0, v3, 11, v101
	v_lshlrev_b32_e32 v0, 2, v0
	v_mov_b32_e32 v4, 0
	v_mov_b32_e32 v5, 0
	v_mov_b32_e32 v6, 0
	v_mov_b32_e32 v7, 0
	v_mov_b32_e32 v8, 0
	v_mov_b32_e32 v9, 0
	v_mov_b32_e32 v10, 0
	v_mov_b32_e32 v11, 0
	v_mov_b32_e32 v12, 0
	v_mov_b32_e32 v13, 0
	v_mov_b32_e32 v14, 0
	v_mov_b32_e32 v15, 0
	v_mov_b32_e32 v16, 0
	v_mov_b32_e32 v17, 0
	v_mov_b32_e32 v18, 0
	v_mov_b32_e32 v19, 0
	v_mov_b32_e32 v20, 0
	v_mov_b32_e32 v21, 0
	v_mov_b32_e32 v22, 0
	v_mov_b32_e32 v23, 0
	v_mov_b32_e32 v24, 0
	v_mov_b32_e32 v25, 0
	v_mov_b32_e32 v26, 0
	v_mov_b32_e32 v27, 0
	v_mov_b32_e32 v28, 0
	v_mov_b32_e32 v29, 0
	v_mov_b32_e32 v30, 0
	v_mov_b32_e32 v31, 0
	v_mov_b32_e32 v32, 0
	v_mov_b32_e32 v33, 0
	v_mov_b32_e32 v34, 0
	v_mov_b32_e32 v35, 0
	s_and_saveexec_b64 s[6:7], s[4:5]
	s_cbranch_execz .Lp2_skip
	v_mov_b32_e32 v1, v2
	v_lshl_add_u64 v[126:127], v[82:83], 0, v[0:1]
	v_add_co_u32_e32 v128, vcc, 0x1000, v126
	s_nop 1
	v_addc_co_u32_e32 v129, vcc, 0, v127, vcc
	global_load_dwordx4 v[130:133], v[126:127], off
	global_load_dwordx4 v[134:137], v[126:127], off offset:16
	global_load_dwordx4 v[138:141], v[126:127], off offset:1024
	global_load_dwordx4 v[142:145], v[126:127], off offset:1040
	global_load_dwordx4 v[146:149], v[126:127], off offset:2048
	global_load_dwordx4 v[150:153], v[126:127], off offset:2064
	global_load_dwordx4 v[154:157], v[126:127], off offset:3072
	global_load_dwordx4 v[158:161], v[126:127], off offset:3088
	global_load_dwordx4 v[162:165], v[128:129], off
	global_load_dwordx4 v[166:169], v[128:129], off offset:16
	global_load_dwordx4 v[170:173], v[128:129], off offset:1024
	global_load_dwordx4 v[174:177], v[128:129], off offset:1040
	global_load_dwordx4 v[178:181], v[128:129], off offset:2048
	global_load_dwordx4 v[182:185], v[128:129], off offset:2064
	global_load_dwordx4 v[186:189], v[128:129], off offset:3072
	global_load_dwordx4 v[190:193], v[128:129], off offset:3088
	s_waitcnt vmcnt(0)
	v_cvt_pkrtz_f16_f32 v8, v130, v131
	v_cvt_pkrtz_f16_f32 v9, v132, v133
	v_cvt_pkrtz_f16_f32 v10, v134, v135
	v_cvt_pkrtz_f16_f32 v11, v136, v137
	v_cvt_pkrtz_f16_f32 v12, v138, v139
	v_cvt_pkrtz_f16_f32 v13, v140, v141
	v_cvt_pkrtz_f16_f32 v14, v142, v143
	v_cvt_pkrtz_f16_f32 v15, v144, v145
	v_cvt_pkrtz_f16_f32 v4, v146, v147
	v_cvt_pkrtz_f16_f32 v5, v148, v149
	v_cvt_pkrtz_f16_f32 v6, v150, v151
	v_cvt_pkrtz_f16_f32 v7, v152, v153
	v_cvt_pkrtz_f16_f32 v16, v154, v155
	v_cvt_pkrtz_f16_f32 v17, v156, v157
	v_cvt_pkrtz_f16_f32 v18, v158, v159
	v_cvt_pkrtz_f16_f32 v19, v160, v161
	v_cvt_pkrtz_f16_f32 v24, v162, v163
	v_cvt_pkrtz_f16_f32 v25, v164, v165
	v_cvt_pkrtz_f16_f32 v26, v166, v167
	v_cvt_pkrtz_f16_f32 v27, v168, v169
	v_cvt_pkrtz_f16_f32 v28, v170, v171
	v_cvt_pkrtz_f16_f32 v29, v172, v173
	v_cvt_pkrtz_f16_f32 v30, v174, v175
	v_cvt_pkrtz_f16_f32 v31, v176, v177
	v_cvt_pkrtz_f16_f32 v20, v178, v179
	v_cvt_pkrtz_f16_f32 v21, v180, v181
	v_cvt_pkrtz_f16_f32 v22, v182, v183
	v_cvt_pkrtz_f16_f32 v23, v184, v185
	v_cvt_pkrtz_f16_f32 v32, v186, v187
	v_cvt_pkrtz_f16_f32 v33, v188, v189
	v_cvt_pkrtz_f16_f32 v34, v190, v191
	v_cvt_pkrtz_f16_f32 v35, v192, v193

; __device__ __forceinline__ unsigned cvt_pk_bf16(float lo, float hi) { return __builtin_bit_cast(unsigned, __builtin_amdgcn_cvt_pkrtz(lo, hi)); }
; __device__ __forceinline__ void phase_ssm2(int wid_s, unsigned char* shm, const float* US, const float* SSA, const float* SSB, const float* FIN, const float* c_re, const float* c_im, const float* dvec, bf16_t* YG) {
;     ...
;     for (int item = blockIdx.x; item < BATCH * 8 * (NCH / 2); item += gridDim.x) {
;         const int cp = (item >= 256) ? 15 - (item & 15) : (item & 15), gq = (item >> 4) & 7, b = item >> 7, g = gq * 4 + gl, ch = cp * 2 + (wid >> 2);
;         SsmProj P; ssm_proj_load(P, SSB, g, fr, fq);
;         bf16x8 cf[4];
; #pragma unroll
;         for (int ks = 0; ks < 4; ++ks) { const size_t o = ((size_t)g * 16 + fr) * 64 + 16 * ks + 4 * fq; const f32x4 cr = *(const f32x4*)(c_re + o), ci = *(const f32x4*)(c_im + o);
;             const u32x4 w = {cvt_pk_bf16(cr[0], -ci[0]), cvt_pk_bf16(cr[1], -ci[1]), cvt_pk_bf16(cr[2], -ci[2]), cvt_pk_bf16(cr[3], -ci[3])}; cf[ks] = __builtin_bit_cast(bf16x8, w); }
;         const f32x4 A = *(const f32x4*)(SSA + ((size_t)g * 64 + lane) * 4);
;         float sr = 0.f, si = 0.f;
;         for (int c0 = 0; c0 < ch; c0 += 8) {
;             f32x2 f[8];
; #pragma unroll
;             for (int j = 0; j < 8; ++j) { const int c = (c0 + j < NCH) ? c0 + j : NCH - 1; f[j] = *(const f32x2*)(FIN + ((size_t)((b * 32 + g) * NCH + c) * 64 + lane) * 2); }
; #pragma unroll
;             for (int j = 0; j < 8; ++j) if (c0 + j < ch) { const float nr = A[2] * sr - A[3] * si + f[j].x, ni = A[2] * si + A[3] * sr + f[j].y; sr = nr; si = ni; }
;         }
.LBB0_480:
	v_lshlrev_b32_e32 v0, 10, v3
	v_or_b32_e32 v1, v0, v108
	v_lshlrev_b32_e32 v1, 2, v1
	global_load_dwordx4 v[56:59], v1, s[8:9]
	global_load_dwordx4 v[52:55], v1, s[8:9] offset:64
	global_load_dwordx4 v[68:71], v1, s[14:15]
	global_load_dwordx4 v[60:63], v1, s[14:15] offset:64
	global_load_dwordx4 v[44:47], v1, s[8:9] offset:128
	global_load_dwordx4 v[40:43], v1, s[8:9] offset:192
	global_load_dwordx4 v[64:67], v1, s[14:15] offset:128
	global_load_dwordx4 v[48:51], v1, s[14:15] offset:192
	v_lshl_or_b32 v0, v106, 2, v0
	v_mov_b32_e32 v1, v2
	v_lshl_add_u64 v[0:1], s[68:69], 0, v[0:1]
	flat_load_dwordx4 v[36:39], v[0:1]
	s_lshl_b32 s6, s10, 1
	s_and_b32 s6, s6, 30
	s_ashr_i32 s18, s10, 7
	s_xor_b32 s7, s6, 30
	s_cmpk_gt_i32 s10, 0xff
	s_cselect_b32 s6, s7, s6
	v_add_u32_e32 v77, s6, v99
	v_cmp_lt_i32_e32 vcc, 0, v77
	v_mov_b32_e32 v100, 0
	v_mov_b32_e32 v98, 0
	s_and_saveexec_b64 s[20:21], vcc
	s_cbranch_execz .LBB0_492
	s_lshl_b32 s6, s18, 10
	v_lshl_or_b32 v0, v3, 5, s6
	v_ashrrev_i32_e32 v1, 31, v0
	v_lshlrev_b64 v[72:73], 9, v[0:1]
	v_lshl_add_u64 v[72:73], v[84:85], 0, v[72:73]
	flat_load_dwordx2 v[72:73], v[72:73]
	v_or_b32_e32 v74, 1, v0
	v_ashrrev_i32_e32 v75, 31, v74
	v_lshlrev_b64 v[74:75], 9, v[74:75]
	v_lshl_add_u64 v[74:75], v[84:85], 0, v[74:75]
	flat_load_dwordx2 v[74:75], v[74:75]
	v_or_b32_e32 v78, 2, v0
	v_ashrrev_i32_e32 v79, 31, v78
	v_lshlrev_b64 v[78:79], 9, v[78:79]
	v_lshl_add_u64 v[78:79], v[84:85], 0, v[78:79]
	flat_load_dwordx2 v[78:79], v[78:79]
	v_or_b32_e32 v102, 3, v0
	v_ashrrev_i32_e32 v103, 31, v102
	v_lshlrev_b64 v[102:103], 9, v[102:103]
	v_lshl_add_u64 v[102:103], v[84:85], 0, v[102:103]
	flat_load_dwordx2 v[102:103], v[102:103]
	v_or_b32_e32 v104, 4, v0
	v_ashrrev_i32_e32 v105, 31, v104
	v_lshlrev_b64 v[104:105], 9, v[104:105]
	v_lshl_add_u64 v[104:105], v[84:85], 0, v[104:105]
	flat_load_dwordx2 v[104:105], v[104:105]
	v_or_b32_e32 v112, 5, v0
	v_ashrrev_i32_e32 v113, 31, v112
	v_lshlrev_b64 v[112:113], 9, v[112:113]
	v_lshl_add_u64 v[112:113], v[84:85], 0, v[112:113]
	flat_load_dwordx2 v[112:113], v[112:113]
	v_or_b32_e32 v114, 6, v0
	v_ashrrev_i32_e32 v115, 31, v114
	v_lshlrev_b64 v[114:115], 9, v[114:115]
	v_lshl_add_u64 v[114:115], v[84:85], 0, v[114:115]
	flat_load_dwordx2 v[114:115], v[114:115]
	v_or_b32_e32 v116, 7, v0
	v_ashrrev_i32_e32 v117, 31, v116
	v_lshlrev_b64 v[116:117], 9, v[116:117]
	v_lshl_add_u64 v[116:117], v[84:85], 0, v[116:117]
	flat_load_dwordx2 v[116:117], v[116:117]
	s_waitcnt vmcnt(0) lgkmcnt(0)
	v_mul_f32_e32 v1, 0, v38
	v_mul_f32_e32 v119, 0, v39
	v_sub_f32_e32 v118, v1, v119
	v_fmac_f32_e32 v119, 0, v38
	v_cmp_eq_u32_e32 vcc, 1, v77
	v_pk_add_f32 v[72:73], v[118:119], v[72:73]
	s_nop 0
	v_pk_mul_f32 v[118:119], v[38:39], v[72:73] op_sel:[1,1] op_sel_hi:[0,1]
	v_pk_fma_f32 v[120:121], v[38:39], v[72:73], v[118:119] op_sel_hi:[1,0,1]
	v_pk_fma_f32 v[118:119], v[38:39], v[72:73], v[118:119] op_sel_hi:[1,0,1] neg_lo:[0,0,1] neg_hi:[0,0,1]
	s_nop 0
	v_mov_b32_e32 v119, v121
	v_pk_add_f32 v[74:75], v[74:75], v[118:119]
	s_nop 0
	v_cndmask_b32_e32 v73, v75, v73, vcc
	v_cndmask_b32_e32 v72, v74, v72, vcc
	v_pk_mul_f32 v[74:75], v[38:39], v[72:73]
	v_pk_mul_f32 v[118:119], v[38:39], v[72:73] op_sel:[1,0] op_sel_hi:[0,1]
	v_sub_f32_e32 v1, v74, v75
	v_add_f32_e32 v74, v119, v118
	v_add_f32_e32 v1, v78, v1
	v_add_f32_e32 v74, v79, v74
	v_cmp_lt_u32_e32 vcc, 2, v77
	s_nop 1
	v_cndmask_b32_e32 v73, v73, v74, vcc
	v_cndmask_b32_e32 v1, v72, v1, vcc
	v_mul_f32_e32 v72, v39, v73
	v_mul_f32_e32 v74, v39, v1
	v_fma_f32 v72, v38, v1, -v72
	v_fmac_f32_e32 v74, v38, v73
	v_add_f32_e32 v72, v102, v72
	v_add_f32_e32 v74, v103, v74
	v_cmp_lt_u32_e32 vcc, 3, v77
	s_nop 1
	v_cndmask_b32_e32 v73, v73, v74, vcc
	v_cndmask_b32_e32 v1, v1, v72, vcc
	v_mul_f32_e32 v72, v39, v73
	v_mul_f32_e32 v74, v39, v1
	v_fma_f32 v72, v38, v1, -v72
	v_fmac_f32_e32 v74, v38, v73
	v_add_f32_e32 v72, v104, v72
	v_add_f32_e32 v74, v105, v74
	v_cmp_lt_u32_e32 vcc, 4, v77
	s_nop 1
	v_cndmask_b32_e32 v73, v73, v74, vcc
	v_cndmask_b32_e32 v1, v1, v72, vcc
	v_mul_f32_e32 v72, v39, v73
	v_mul_f32_e32 v74, v39, v1
	v_fma_f32 v72, v38, v1, -v72
	v_fmac_f32_e32 v74, v38, v73
	v_add_f32_e32 v72, v112, v72
	v_add_f32_e32 v74, v113, v74
	v_cmp_lt_u32_e32 vcc, 5, v77
	s_nop 1
	v_cndmask_b32_e32 v73, v73, v74, vcc
	v_cndmask_b32_e32 v1, v1, v72, vcc
	v_mul_f32_e32 v72, v39, v73
	v_mul_f32_e32 v74, v39, v1
	v_fma_f32 v72, v38, v1, -v72
	v_fmac_f32_e32 v74, v38, v73
	v_add_f32_e32 v72, v114, v72
	v_add_f32_e32 v74, v115, v74
	v_cmp_lt_u32_e32 vcc, 6, v77
	s_nop 1
	v_cndmask_b32_e32 v73, v73, v74, vcc
	v_cndmask_b32_e32 v1, v1, v72, vcc
	v_mul_f32_e32 v72, v39, v73
	v_mul_f32_e32 v75, v39, v1
	v_fma_f32 v72, v38, v1, -v72
	v_fmac_f32_e32 v75, v38, v73
	v_add_f32_e32 v74, v116, v72
	v_add_f32_e32 v76, v117, v75
	v_cmp_lt_u32_e32 vcc, 7, v77
	s_nop 1
	v_cndmask_b32_e32 v100, v73, v76, vcc
	v_cndmask_b32_e32 v98, v1, v74, vcc
	v_cmp_lt_u32_e32 vcc, 8, v77
	s_and_saveexec_b64 s[22:23], vcc
	s_cbranch_execz .LBB0_491
; __device__ __forceinline__ void phase_ssm2(int wid_s, unsigned char* shm, const float* US, const float* SSA, const float* SSB, const float* FIN, const float* c_re, const float* c_im, const float* dvec, bf16_t* YG) {
;     ...
;         for (int c0 = 0; c0 < ch; c0 += 8) {
;             f32x2 f[8];
; #pragma unroll
;             for (int j = 0; j < 8; ++j) { const int c = (c0 + j < NCH) ? c0 + j : NCH - 1; f[j] = *(const f32x2*)(FIN + ((size_t)((b * 32 + g) * NCH + c) * 64 + lane) * 2); }
; #pragma unroll
;             for (int j = 0; j < 8; ++j) if (c0 + j < ch) { const float nr = A[2] * sr - A[3] * si + f[j].x, ni = A[2] * si + A[3] * sr + f[j].y; sr = nr; si = ni; }
	v_or_b32_e32 v72, 8, v0
	v_ashrrev_i32_e32 v73, 31, v72
	v_lshlrev_b64 v[72:73], 9, v[72:73]
	v_lshl_add_u64 v[72:73], v[84:85], 0, v[72:73]
	flat_load_dwordx2 v[78:79], v[72:73]
	v_or_b32_e32 v72, 9, v0
	v_ashrrev_i32_e32 v73, 31, v72
	v_lshlrev_b64 v[72:73], 9, v[72:73]
	v_lshl_add_u64 v[72:73], v[84:85], 0, v[72:73]
	flat_load_dwordx2 v[102:103], v[72:73]
	v_or_b32_e32 v72, 10, v0
	v_ashrrev_i32_e32 v73, 31, v72
	v_lshlrev_b64 v[72:73], 9, v[72:73]
	v_lshl_add_u64 v[72:73], v[84:85], 0, v[72:73]
	flat_load_dwordx2 v[104:105], v[72:73]
	v_or_b32_e32 v72, 11, v0
	v_ashrrev_i32_e32 v73, 31, v72
	v_lshlrev_b64 v[72:73], 9, v[72:73]
	v_lshl_add_u64 v[72:73], v[84:85], 0, v[72:73]
	flat_load_dwordx2 v[112:113], v[72:73]
	v_or_b32_e32 v72, 12, v0
	v_ashrrev_i32_e32 v73, 31, v72
	v_lshlrev_b64 v[72:73], 9, v[72:73]
	v_lshl_add_u64 v[72:73], v[84:85], 0, v[72:73]
	flat_load_dwordx2 v[114:115], v[72:73]
	v_or_b32_e32 v72, 13, v0
	v_ashrrev_i32_e32 v73, 31, v72
	v_lshlrev_b64 v[72:73], 9, v[72:73]
	v_lshl_add_u64 v[72:73], v[84:85], 0, v[72:73]
	flat_load_dwordx2 v[116:117], v[72:73]
	v_or_b32_e32 v72, 14, v0
	v_ashrrev_i32_e32 v73, 31, v72
	v_lshlrev_b64 v[72:73], 9, v[72:73]
	v_lshl_add_u64 v[72:73], v[84:85], 0, v[72:73]
	flat_load_dwordx2 v[118:119], v[72:73]
	v_or_b32_e32 v72, 15, v0
	v_ashrrev_i32_e32 v73, 31, v72
	v_lshlrev_b64 v[72:73], 9, v[72:73]
	v_lshl_add_u64 v[72:73], v[84:85], 0, v[72:73]
	flat_load_dwordx2 v[120:121], v[72:73]
	v_pk_mov_b32 v[72:73], v[38:39], v[38:39] op_sel:[1,0]
	v_cmp_eq_u32_e32 vcc, 9, v77
	v_pk_mul_f32 v[122:123], v[72:73], v[76:77] op_sel_hi:[1,0]
	s_nop 0
	v_pk_fma_f32 v[124:125], v[38:39], v[74:75], v[122:123] op_sel_hi:[1,0,1]
	v_pk_fma_f32 v[74:75], v[38:39], v[74:75], v[122:123] op_sel_hi:[1,0,1] neg_lo:[0,0,1] neg_hi:[0,0,1]
	s_nop 0
	v_mov_b32_e32 v75, v125
	s_waitcnt vmcnt(0) lgkmcnt(0)
	v_pk_add_f32 v[74:75], v[74:75], v[78:79]
	s_nop 0
	v_pk_mul_f32 v[78:79], v[72:73], v[74:75] op_sel:[0,1]
	s_nop 0
	v_pk_fma_f32 v[122:123], v[38:39], v[74:75], v[78:79] op_sel_hi:[1,0,1]
	v_pk_fma_f32 v[78:79], v[38:39], v[74:75], v[78:79] op_sel_hi:[1,0,1] neg_lo:[0,0,1] neg_hi:[0,0,1]
	s_nop 0
	v_mov_b32_e32 v79, v123
	v_pk_add_f32 v[78:79], v[102:103], v[78:79]
	s_nop 0
	v_cndmask_b32_e32 v76, v79, v75, vcc
	v_cndmask_b32_e32 v74, v78, v74, vcc
	v_pk_mul_f32 v[78:79], v[72:73], v[76:77] op_sel_hi:[1,0]
	v_cmp_lt_u32_e32 vcc, 10, v77
	v_pk_fma_f32 v[102:103], v[38:39], v[74:75], v[78:79] op_sel_hi:[1,0,1]
	v_pk_fma_f32 v[78:79], v[38:39], v[74:75], v[78:79] op_sel_hi:[1,0,1] neg_lo:[0,0,1] neg_hi:[0,0,1]
	s_nop 0
	v_mov_b32_e32 v79, v103
	v_pk_add_f32 v[78:79], v[104:105], v[78:79]
	s_nop 0
	v_cndmask_b32_e32 v76, v76, v79, vcc
	v_cndmask_b32_e32 v74, v74, v78, vcc
	v_pk_mul_f32 v[78:79], v[72:73], v[76:77] op_sel_hi:[1,0]
	v_cmp_lt_u32_e32 vcc, 11, v77
	v_pk_fma_f32 v[102:103], v[38:39], v[74:75], v[78:79] op_sel_hi:[1,0,1]
	v_pk_fma_f32 v[78:79], v[38:39], v[74:75], v[78:79] op_sel_hi:[1,0,1] neg_lo:[0,0,1] neg_hi:[0,0,1]
	s_nop 0
	v_mov_b32_e32 v79, v103
	v_pk_add_f32 v[78:79], v[112:113], v[78:79]
	s_nop 0
	v_cndmask_b32_e32 v75, v76, v79, vcc
	v_cndmask_b32_e32 v74, v74, v78, vcc
	v_pk_mul_f32 v[78:79], v[38:39], v[74:75]
	v_pk_mul_f32 v[102:103], v[72:73], v[74:75]
	v_sub_f32_e32 v1, v78, v79
	v_add_f32_e32 v76, v103, v102
	v_add_f32_e32 v1, v114, v1
	v_add_f32_e32 v76, v115, v76
	v_cmp_lt_u32_e32 vcc, 12, v77
	s_nop 1
	v_cndmask_b32_e32 v75, v75, v76, vcc
	v_cndmask_b32_e32 v1, v74, v1, vcc
	v_mul_f32_e32 v74, v39, v75
	v_mul_f32_e32 v76, v39, v1
	v_fma_f32 v74, v38, v1, -v74
	v_fmac_f32_e32 v76, v38, v75
	v_add_f32_e32 v74, v116, v74
	v_add_f32_e32 v76, v117, v76
	v_cmp_lt_u32_e32 vcc, 13, v77
	s_nop 1
	v_cndmask_b32_e32 v75, v75, v76, vcc
	v_cndmask_b32_e32 v1, v1, v74, vcc
	v_mul_f32_e32 v74, v39, v75
	v_mul_f32_e32 v76, v39, v1
	v_fma_f32 v74, v38, v1, -v74
	v_fmac_f32_e32 v76, v38, v75
	v_add_f32_e32 v74, v118, v74
	v_add_f32_e32 v76, v119, v76
	v_cmp_lt_u32_e32 vcc, 14, v77
	s_nop 1
	v_cndmask_b32_e32 v75, v75, v76, vcc
	v_cndmask_b32_e32 v1, v1, v74, vcc
	v_mul_f32_e32 v74, v39, v75
	v_mul_f32_e32 v76, v39, v1
	v_fma_f32 v74, v38, v1, -v74
	v_fmac_f32_e32 v76, v38, v75
	v_add_f32_e32 v74, v120, v74
	v_add_f32_e32 v76, v121, v76
	v_cmp_lt_u32_e32 vcc, 15, v77
	s_nop 1
	v_cndmask_b32_e32 v100, v75, v76, vcc
	v_cndmask_b32_e32 v98, v1, v74, vcc
	v_cmp_lt_u32_e32 vcc, 16, v77
	s_and_saveexec_b64 s[24:25], vcc
	s_cbranch_execz .LBB0_490
; __device__ __forceinline__ void phase_ssm2(int wid_s, unsigned char* shm, const float* US, const float* SSA, const float* SSB, const float* FIN, const float* c_re, const float* c_im, const float* dvec, bf16_t* YG) {
;     ...
;         for (int c0 = 0; c0 < ch; c0 += 8) {
;             f32x2 f[8];
; #pragma unroll
;             for (int j = 0; j < 8; ++j) { const int c = (c0 + j < NCH) ? c0 + j : NCH - 1; f[j] = *(const f32x2*)(FIN + ((size_t)((b * 32 + g) * NCH + c) * 64 + lane) * 2); }
; #pragma unroll
;             for (int j = 0; j < 8; ++j) if (c0 + j < ch) { const float nr = A[2] * sr - A[3] * si + f[j].x, ni = A[2] * si + A[3] * sr + f[j].y; sr = nr; si = ni; }
	v_or_b32_e32 v78, 16, v0
	v_ashrrev_i32_e32 v79, 31, v78
	v_lshlrev_b64 v[78:79], 9, v[78:79]
	v_lshl_add_u64 v[78:79], v[84:85], 0, v[78:79]
	flat_load_dwordx2 v[78:79], v[78:79]
	v_or_b32_e32 v102, 17, v0
	v_ashrrev_i32_e32 v103, 31, v102
	v_lshlrev_b64 v[102:103], 9, v[102:103]
	v_lshl_add_u64 v[102:103], v[84:85], 0, v[102:103]
	flat_load_dwordx2 v[102:103], v[102:103]
	v_or_b32_e32 v104, 18, v0
	v_ashrrev_i32_e32 v105, 31, v104
	v_lshlrev_b64 v[104:105], 9, v[104:105]
	v_lshl_add_u64 v[104:105], v[84:85], 0, v[104:105]
	flat_load_dwordx2 v[104:105], v[104:105]
	v_or_b32_e32 v112, 19, v0
	v_ashrrev_i32_e32 v113, 31, v112
	v_lshlrev_b64 v[112:113], 9, v[112:113]
	v_lshl_add_u64 v[112:113], v[84:85], 0, v[112:113]
	flat_load_dwordx2 v[112:113], v[112:113]
	v_or_b32_e32 v114, 20, v0
	v_ashrrev_i32_e32 v115, 31, v114
	v_lshlrev_b64 v[114:115], 9, v[114:115]
	v_lshl_add_u64 v[114:115], v[84:85], 0, v[114:115]
	flat_load_dwordx2 v[114:115], v[114:115]
	v_or_b32_e32 v116, 21, v0
	v_ashrrev_i32_e32 v117, 31, v116
	v_lshlrev_b64 v[116:117], 9, v[116:117]
	v_lshl_add_u64 v[116:117], v[84:85], 0, v[116:117]
	flat_load_dwordx2 v[116:117], v[116:117]
	v_or_b32_e32 v118, 22, v0
	v_ashrrev_i32_e32 v119, 31, v118
	v_lshlrev_b64 v[118:119], 9, v[118:119]
	v_lshl_add_u64 v[118:119], v[84:85], 0, v[118:119]
	flat_load_dwordx2 v[118:119], v[118:119]
	v_or_b32_e32 v120, 23, v0
	v_ashrrev_i32_e32 v121, 31, v120
	v_lshlrev_b64 v[120:121], 9, v[120:121]
	v_lshl_add_u64 v[120:121], v[84:85], 0, v[120:121]
	flat_load_dwordx2 v[120:121], v[120:121]
	v_pk_mul_f32 v[122:123], v[72:73], v[76:77] op_sel_hi:[1,0]
	v_cmp_eq_u32_e32 vcc, 17, v77
	v_pk_fma_f32 v[124:125], v[38:39], v[74:75], v[122:123] op_sel_hi:[1,0,1]
	v_pk_fma_f32 v[74:75], v[38:39], v[74:75], v[122:123] op_sel_hi:[1,0,1] neg_lo:[0,0,1] neg_hi:[0,0,1]
	s_nop 0
	v_mov_b32_e32 v75, v125
	s_waitcnt vmcnt(0) lgkmcnt(0)
	v_pk_add_f32 v[74:75], v[74:75], v[78:79]
	s_nop 0
	v_pk_mul_f32 v[78:79], v[72:73], v[74:75] op_sel:[0,1]
	s_nop 0
	v_pk_fma_f32 v[122:123], v[38:39], v[74:75], v[78:79] op_sel_hi:[1,0,1]
	v_pk_fma_f32 v[78:79], v[38:39], v[74:75], v[78:79] op_sel_hi:[1,0,1] neg_lo:[0,0,1] neg_hi:[0,0,1]
	s_nop 0
	v_mov_b32_e32 v79, v123
	v_pk_add_f32 v[78:79], v[102:103], v[78:79]
	s_nop 0
	v_cndmask_b32_e32 v76, v79, v75, vcc
	v_cndmask_b32_e32 v74, v78, v74, vcc
	v_pk_mul_f32 v[78:79], v[72:73], v[76:77] op_sel_hi:[1,0]
	v_cmp_lt_u32_e32 vcc, 18, v77
	v_pk_fma_f32 v[102:103], v[38:39], v[74:75], v[78:79] op_sel_hi:[1,0,1]
	v_pk_fma_f32 v[78:79], v[38:39], v[74:75], v[78:79] op_sel_hi:[1,0,1] neg_lo:[0,0,1] neg_hi:[0,0,1]
	s_nop 0
	v_mov_b32_e32 v79, v103
	v_pk_add_f32 v[78:79], v[104:105], v[78:79]
	s_nop 0
	v_cndmask_b32_e32 v76, v76, v79, vcc
	v_cndmask_b32_e32 v74, v74, v78, vcc
	v_pk_mul_f32 v[78:79], v[72:73], v[76:77] op_sel_hi:[1,0]
	v_cmp_lt_u32_e32 vcc, 19, v77
	v_pk_fma_f32 v[102:103], v[38:39], v[74:75], v[78:79] op_sel_hi:[1,0,1]
	v_pk_fma_f32 v[78:79], v[38:39], v[74:75], v[78:79] op_sel_hi:[1,0,1] neg_lo:[0,0,1] neg_hi:[0,0,1]
	s_nop 0
	v_mov_b32_e32 v79, v103
	v_pk_add_f32 v[78:79], v[112:113], v[78:79]
	s_nop 0
	v_cndmask_b32_e32 v75, v76, v79, vcc
	v_cndmask_b32_e32 v74, v74, v78, vcc
	v_pk_mul_f32 v[78:79], v[38:39], v[74:75]
	v_pk_mul_f32 v[102:103], v[72:73], v[74:75]
	v_sub_f32_e32 v1, v78, v79
	v_add_f32_e32 v76, v103, v102
	v_add_f32_e32 v1, v114, v1
	v_add_f32_e32 v76, v115, v76
	v_cmp_lt_u32_e32 vcc, 20, v77
	s_nop 1
	v_cndmask_b32_e32 v75, v75, v76, vcc
	v_cndmask_b32_e32 v1, v74, v1, vcc
	v_mul_f32_e32 v74, v39, v75
	v_mul_f32_e32 v76, v39, v1
	v_fma_f32 v74, v38, v1, -v74
	v_fmac_f32_e32 v76, v38, v75
	v_add_f32_e32 v74, v116, v74
	v_add_f32_e32 v76, v117, v76
	v_cmp_lt_u32_e32 vcc, 21, v77
	s_nop 1
	v_cndmask_b32_e32 v75, v75, v76, vcc
	v_cndmask_b32_e32 v1, v1, v74, vcc
	v_mul_f32_e32 v74, v39, v75
	v_mul_f32_e32 v76, v39, v1
	v_fma_f32 v74, v38, v1, -v74
	v_fmac_f32_e32 v76, v38, v75
	v_add_f32_e32 v74, v118, v74
	v_add_f32_e32 v76, v119, v76
	v_cmp_lt_u32_e32 vcc, 22, v77
	s_nop 1
	v_cndmask_b32_e32 v75, v75, v76, vcc
	v_cndmask_b32_e32 v1, v1, v74, vcc
	v_mul_f32_e32 v74, v39, v75
	v_mul_f32_e32 v76, v39, v1
	v_fma_f32 v74, v38, v1, -v74
	v_fmac_f32_e32 v76, v38, v75
	v_add_f32_e32 v74, v120, v74
	v_add_f32_e32 v76, v121, v76
	v_cmp_lt_u32_e32 vcc, 23, v77
	s_nop 1
	v_cndmask_b32_e32 v100, v75, v76, vcc
	v_cndmask_b32_e32 v98, v1, v74, vcc
	v_cmp_lt_u32_e32 vcc, 24, v77
	s_and_saveexec_b64 s[26:27], vcc
	s_cbranch_execz .LBB0_489
; __device__ __forceinline__ void phase_ssm2(int wid_s, unsigned char* shm, const float* US, const float* SSA, const float* SSB, const float* FIN, const float* c_re, const float* c_im, const float* dvec, bf16_t* YG) {
;     ...
;         for (int c0 = 0; c0 < ch; c0 += 8) {
;             f32x2 f[8];
; #pragma unroll
;             for (int j = 0; j < 8; ++j) { const int c = (c0 + j < NCH) ? c0 + j : NCH - 1; f[j] = *(const f32x2*)(FIN + ((size_t)((b * 32 + g) * NCH + c) * 64 + lane) * 2); }
; #pragma unroll
;             for (int j = 0; j < 8; ++j) if (c0 + j < ch) { const float nr = A[2] * sr - A[3] * si + f[j].x, ni = A[2] * si + A[3] * sr + f[j].y; sr = nr; si = ni; }
	v_or_b32_e32 v78, 24, v0
	v_ashrrev_i32_e32 v79, 31, v78
	v_lshlrev_b64 v[78:79], 9, v[78:79]
	v_lshl_add_u64 v[78:79], v[84:85], 0, v[78:79]
	flat_load_dwordx2 v[78:79], v[78:79]
	v_or_b32_e32 v102, 25, v0
	v_ashrrev_i32_e32 v103, 31, v102
	v_lshlrev_b64 v[102:103], 9, v[102:103]
	v_lshl_add_u64 v[102:103], v[84:85], 0, v[102:103]
	flat_load_dwordx2 v[102:103], v[102:103]
	v_or_b32_e32 v104, 26, v0
	v_ashrrev_i32_e32 v105, 31, v104
	v_lshlrev_b64 v[104:105], 9, v[104:105]
	v_lshl_add_u64 v[104:105], v[84:85], 0, v[104:105]
	flat_load_dwordx2 v[104:105], v[104:105]
	v_or_b32_e32 v112, 27, v0
	v_ashrrev_i32_e32 v113, 31, v112
	v_lshlrev_b64 v[112:113], 9, v[112:113]
	v_lshl_add_u64 v[112:113], v[84:85], 0, v[112:113]
	flat_load_dwordx2 v[112:113], v[112:113]
	v_or_b32_e32 v114, 28, v0
	v_ashrrev_i32_e32 v115, 31, v114
	v_lshlrev_b64 v[114:115], 9, v[114:115]
	v_lshl_add_u64 v[114:115], v[84:85], 0, v[114:115]
	flat_load_dwordx2 v[114:115], v[114:115]
	v_or_b32_e32 v116, 29, v0
	v_ashrrev_i32_e32 v117, 31, v116
	v_lshlrev_b64 v[116:117], 9, v[116:117]
	v_lshl_add_u64 v[116:117], v[84:85], 0, v[116:117]
	flat_load_dwordx2 v[116:117], v[116:117]
	v_or_b32_e32 v118, 30, v0
	v_ashrrev_i32_e32 v119, 31, v118
	v_lshlrev_b64 v[118:119], 9, v[118:119]
	v_lshl_add_u64 v[118:119], v[84:85], 0, v[118:119]
	flat_load_dwordx2 v[118:119], v[118:119]
	v_or_b32_e32 v0, 31, v0
	v_ashrrev_i32_e32 v1, 31, v0
	v_lshlrev_b64 v[0:1], 9, v[0:1]
	v_lshl_add_u64 v[0:1], v[84:85], 0, v[0:1]
	flat_load_dwordx2 v[0:1], v[0:1]
	v_pk_mul_f32 v[120:121], v[72:73], v[76:77] op_sel_hi:[1,0]
	v_cmp_eq_u32_e32 vcc, 25, v77
	v_pk_fma_f32 v[122:123], v[38:39], v[74:75], v[120:121] op_sel_hi:[1,0,1]
	v_pk_fma_f32 v[74:75], v[38:39], v[74:75], v[120:121] op_sel_hi:[1,0,1] neg_lo:[0,0,1] neg_hi:[0,0,1]
	s_nop 0
	v_mov_b32_e32 v75, v123
	s_waitcnt vmcnt(0) lgkmcnt(0)
	v_pk_add_f32 v[74:75], v[74:75], v[78:79]
	s_nop 0
	v_pk_mul_f32 v[78:79], v[72:73], v[74:75] op_sel:[0,1]
	s_nop 0
	v_pk_fma_f32 v[120:121], v[38:39], v[74:75], v[78:79] op_sel_hi:[1,0,1]
	v_pk_fma_f32 v[78:79], v[38:39], v[74:75], v[78:79] op_sel_hi:[1,0,1] neg_lo:[0,0,1] neg_hi:[0,0,1]
	s_nop 0
	v_mov_b32_e32 v79, v121
	v_pk_add_f32 v[78:79], v[102:103], v[78:79]
	s_nop 0
	v_cndmask_b32_e32 v76, v79, v75, vcc
	v_cndmask_b32_e32 v74, v78, v74, vcc
	v_pk_mul_f32 v[78:79], v[72:73], v[76:77] op_sel_hi:[1,0]
	v_cmp_lt_u32_e32 vcc, 26, v77
	v_pk_fma_f32 v[102:103], v[38:39], v[74:75], v[78:79] op_sel_hi:[1,0,1]
	v_pk_fma_f32 v[78:79], v[38:39], v[74:75], v[78:79] op_sel_hi:[1,0,1] neg_lo:[0,0,1] neg_hi:[0,0,1]
	s_nop 0
	v_mov_b32_e32 v79, v103
	v_pk_add_f32 v[78:79], v[104:105], v[78:79]
	s_nop 0
	v_cndmask_b32_e32 v76, v76, v79, vcc
	v_cndmask_b32_e32 v74, v74, v78, vcc
	v_pk_mul_f32 v[78:79], v[72:73], v[76:77] op_sel_hi:[1,0]
	v_cmp_lt_u32_e32 vcc, 27, v77
	v_pk_fma_f32 v[102:103], v[38:39], v[74:75], v[78:79] op_sel_hi:[1,0,1]
	v_pk_fma_f32 v[78:79], v[38:39], v[74:75], v[78:79] op_sel_hi:[1,0,1] neg_lo:[0,0,1] neg_hi:[0,0,1]
	s_nop 0
	v_mov_b32_e32 v79, v103
	v_pk_add_f32 v[78:79], v[112:113], v[78:79]
	s_nop 0
	v_cndmask_b32_e32 v75, v76, v79, vcc
	v_cndmask_b32_e32 v74, v74, v78, vcc
	v_pk_mul_f32 v[78:79], v[38:39], v[74:75]
	v_pk_mul_f32 v[102:103], v[72:73], v[74:75]
	v_sub_f32_e32 v76, v78, v79
	v_add_f32_e32 v78, v103, v102
	v_add_f32_e32 v76, v114, v76
	v_add_f32_e32 v78, v115, v78
	v_cmp_lt_u32_e32 vcc, 28, v77
	s_nop 1
	v_cndmask_b32_e32 v75, v75, v78, vcc
	v_cndmask_b32_e32 v74, v74, v76, vcc
	v_mul_f32_e32 v76, v39, v75
	v_mul_f32_e32 v78, v39, v74
	v_fma_f32 v76, v38, v74, -v76
	v_fmac_f32_e32 v78, v38, v75
	v_add_f32_e32 v76, v116, v76
	v_add_f32_e32 v78, v117, v78
	v_cmp_lt_u32_e32 vcc, 29, v77
	s_nop 1
	v_cndmask_b32_e32 v75, v75, v78, vcc
	v_cndmask_b32_e32 v74, v74, v76, vcc
	v_mul_f32_e32 v76, v39, v75
	v_mul_f32_e32 v78, v39, v74
	v_fma_f32 v76, v38, v74, -v76
	v_fmac_f32_e32 v78, v38, v75
	v_add_f32_e32 v76, v118, v76
	v_add_f32_e32 v78, v119, v78
	v_cmp_lt_u32_e32 vcc, 30, v77
	s_nop 1
	v_cndmask_b32_e32 v75, v75, v78, vcc
	v_cndmask_b32_e32 v74, v74, v76, vcc
	v_mul_f32_e32 v76, v39, v75
	v_mul_f32_e32 v78, v39, v74
	v_fma_f32 v76, v38, v74, -v76
	v_fmac_f32_e32 v78, v38, v75
	v_add_f32_e32 v76, v0, v76
	v_add_f32_e32 v78, v1, v78
	v_cmp_lt_u32_e32 vcc, 31, v77
	s_nop 1
	v_cndmask_b32_e32 v100, v75, v78, vcc
	v_cndmask_b32_e32 v98, v74, v76, vcc
	v_cmp_lt_u32_e32 vcc, 32, v77
	s_and_saveexec_b64 s[28:29], vcc
	s_cbranch_execz .LBB0_488
	v_mov_b32_e32 v74, v1
	s_mov_b32 s19, 32
	s_mov_b64 s[30:31], 0

; __device__ __forceinline__ unsigned cvt_pk_bf16(float lo, float hi) { return __builtin_bit_cast(unsigned, __builtin_amdgcn_cvt_pkrtz(lo, hi)); }
; __device__ __forceinline__ f32x4 mfma16(bf16x8 a, bf16x8 b, f32x4 c) { return __builtin_amdgcn_mfma_f32_16x16x32_f16(__builtin_bit_cast(f16x8, a), __builtin_bit_cast(f16x8, b), c, 0, 0, 0); }
; __device__ __forceinline__ void wave_lds_fence() { asm volatile("s_waitcnt lgkmcnt(0)" ::: "memory"); __builtin_amdgcn_wave_barrier(); }
; __device__ __forceinline__ void ssm_proj16(const SsmProj& P, u32x4 uw, float* X, int fr, int fq) {
;     const bf16x8 uf = __builtin_bit_cast(bf16x8, uw);
; #pragma unroll
;     for (int nt = 0; nt < 8; ++nt) { f32x4 d = mfma16(uf, P.bf[nt], (f32x4){0.f, 0.f, 0.f, 0.f}); asm volatile("" :: "v"(uf), "v"(P.bf[nt]), "v"(d));
; #pragma unroll
;         for (int r = 0; r < 4; ++r) X[(4 * fq + r) * 132 + 16 * nt + fr] = d[r]; }
; }
; __device__ __forceinline__ void phase_ssm2(int wid_s, unsigned char* shm, const float* US, const float* SSA, const float* SSB, const float* FIN, const float* c_re, const float* c_im, const float* dvec, bf16_t* YG) {
;     ...
;             const u32x4 w = {cvt_pk_bf16(cr[0], -ci[0]), cvt_pk_bf16(cr[1], -ci[1]), cvt_pk_bf16(cr[2], -ci[2]), cvt_pk_bf16(cr[3], -ci[3])}; cf[ks] = __builtin_bit_cast(bf16x8, w); }
;         const f32x4 A = *(const f32x4*)(SSA + ((size_t)g * 64 + lane) * 4);
;         float sr = 0.f, si = 0.f;
;         for (int c0 = 0; c0 < ch; c0 += 8) {
;             f32x2 f[8];
; #pragma unroll
;             for (int j = 0; j < 8; ++j) { const int c = (c0 + j < NCH) ? c0 + j : NCH - 1; f[j] = *(const f32x2*)(FIN + ((size_t)((b * 32 + g) * NCH + c) * 64 + lane) * 2); }
; #pragma unroll
;             for (int j = 0; j < 8; ++j) if (c0 + j < ch) { const float nr = A[2] * sr - A[3] * si + f[j].x, ni = A[2] * si + A[3] * sr + f[j].y; sr = nr; si = ni; }
;         }
;         const f32x4 dv = *(const f32x4*)(dvec + g * 16 + 4 * fq);
;         u32x4 uw = ssm_u_load(US, (size_t)b * SEQ + ch * LCH, g, fr, fq);
;         for (int sub = 0; sub < 4; ++sub) {
;             const size_t tok0 = (size_t)b * SEQ + ch * LCH + sub * 16;
;             wave_lds_fence();
;             ssm_proj16(P, uw, X, fr, fq);
;             if (sub < 3) uw = ssm_u_load(US, tok0 + 16, g, fr, fq);
.LBB0_494:
	s_or_b64 exec, exec, s[6:7]
	v_mov_b32_e32 v105, v2
	v_cvt_pkrtz_f16_f32 v56, v56, -v68
	v_cvt_pkrtz_f16_f32 v57, v57, -v69
	v_cvt_pkrtz_f16_f32 v58, v58, -v70
	v_cvt_pkrtz_f16_f32 v59, v59, -v71
	v_cvt_pkrtz_f16_f32 v52, v52, -v60
	v_cvt_pkrtz_f16_f32 v53, v53, -v61
	v_cvt_pkrtz_f16_f32 v54, v54, -v62
	v_cvt_pkrtz_f16_f32 v55, v55, -v63
	v_cvt_pkrtz_f16_f32 v44, v44, -v64
	v_cvt_pkrtz_f16_f32 v45, v45, -v65
	v_cvt_pkrtz_f16_f32 v46, v46, -v66
	v_cvt_pkrtz_f16_f32 v47, v47, -v67
	v_cvt_pkrtz_f16_f32 v38, v40, -v48
	v_cvt_pkrtz_f16_f32 v39, v41, -v49
	v_cvt_pkrtz_f16_f32 v40, v42, -v50
	v_cvt_pkrtz_f16_f32 v41, v43, -v51
	v_lshl_add_u64 v[0:1], v[88:89], 0, v[104:105]
	v_lshl_add_u64 v[42:43], v[90:91], 0, v[104:105]
	v_lshl_add_u64 v[60:61], v[92:93], 0, v[104:105]
	s_mov_b32 s18, 0
	s_waitcnt vmcnt(0)
.LBB0_495:
	s_waitcnt lgkmcnt(0)
	v_mfma_f32_16x16x32_f16 v[62:65], v[76:79], v[8:11], 0
	v_add_u32_e32 v3, 0x400, v107
	s_waitcnt lgkmcnt(0)
	s_cmp_eq_u32 s18, 3
	s_cselect_b64 vcc, -1, 0
	s_nop 4
	ds_write2_b32 v107, v62, v63 offset1:132
	ds_write2_b32 v3, v64, v65 offset0:8 offset1:140
	v_mfma_f32_16x16x32_f16 v[62:65], v[76:79], v[12:15], 0
	s_nop 7
	ds_write2_b32 v107, v62, v63 offset0:16 offset1:148
	ds_write2_b32 v3, v64, v65 offset0:24 offset1:156
	v_mfma_f32_16x16x32_f16 v[62:65], v[76:79], v[4:7], 0
	s_nop 7
	ds_write2_b32 v107, v62, v63 offset0:32 offset1:164
	ds_write2_b32 v3, v64, v65 offset0:40 offset1:172
	v_mfma_f32_16x16x32_f16 v[62:65], v[76:79], v[16:19], 0
	s_nop 7
	ds_write2_b32 v107, v62, v63 offset0:48 offset1:180
	ds_write2_b32 v3, v64, v65 offset0:56 offset1:188
	v_mfma_f32_16x16x32_f16 v[62:65], v[76:79], v[24:27], 0
	s_nop 7
	ds_write2_b32 v107, v62, v63 offset0:64 offset1:196
	ds_write2_b32 v3, v64, v65 offset0:72 offset1:204
	v_mfma_f32_16x16x32_f16 v[62:65], v[76:79], v[28:31], 0
	s_nop 7
	ds_write2_b32 v107, v62, v63 offset0:80 offset1:212
	ds_write2_b32 v3, v64, v65 offset0:88 offset1:220
	v_mfma_f32_16x16x32_f16 v[62:65], v[76:79], v[20:23], 0
	s_nop 7
	ds_write2_b32 v107, v62, v63 offset0:96 offset1:228
	ds_write2_b32 v3, v64, v65 offset0:104 offset1:236
	v_mfma_f32_16x16x32_f16 v[62:65], v[76:79], v[32:35], 0
	v_lshl_or_b32 v48, s18, 4, v102
	v_mov_b32_e32 v49, v103
	v_cndmask_b32_e32 v79, 0, v79, vcc
	s_nor_b64 s[20:21], s[2:3], vcc
	v_cndmask_b32_e32 v78, 0, v78, vcc
	v_cndmask_b32_e32 v77, 0, v77, vcc
	v_cndmask_b32_e32 v76, 0, v76, vcc
	s_nop 0
	ds_write2_b32 v107, v62, v63 offset0:112 offset1:244
	ds_write2_b32 v3, v64, v65 offset0:120 offset1:252
	s_and_saveexec_b64 s[6:7], s[20:21]
	s_cbranch_execz .LBB0_497
	v_lshl_add_u64 v[50:51], v[48:49], 0, v[94:95]
	v_lshlrev_b64 v[50:51], 10, v[50:51]
	v_lshl_add_u64 v[50:51], v[0:1], 0, v[50:51]
	flat_load_dwordx4 v[76:79], v[50:51]

; #define LAS __attribute__((address_space(3)))
; __device__ __forceinline__ float h2f(unsigned h) { float r; asm volatile("v_cvt_f32_f16 %0, %1" : "=v"(r) : "v"(h)); return r; }
; __device__ __forceinline__ unsigned cvt_pk_bf16(float lo, float hi) { return __builtin_bit_cast(unsigned, __builtin_amdgcn_cvt_pkrtz(lo, hi)); }
; __device__ __forceinline__ f32x4 mfma16(bf16x8 a, bf16x8 b, f32x4 c) { return __builtin_amdgcn_mfma_f32_16x16x32_f16(__builtin_bit_cast(f16x8, a), __builtin_bit_cast(f16x8, b), c, 0, 0, 0); }
; __device__ __forceinline__ u32x2 pack4(f32x4 v) { u32x2 r; r.x = cvt_pk_bf16(v[0], v[1]); r.y = cvt_pk_bf16(v[2], v[3]); return r; }
; __device__ __forceinline__ float gelu_tanh(float y) { const float u = 0.7978845608028654f * (y + 0.044715f * y * y * y); return y * __builtin_amdgcn_rcpf(1.0f + __expf(-2.0f * u)); }
; __device__ __forceinline__ void wave_lds_fence() { asm volatile("s_waitcnt lgkmcnt(0)" ::: "memory"); __builtin_amdgcn_wave_barrier(); }
; __device__ __forceinline__ void phase_ssm2(int wid_s, unsigned char* shm, const float* US, const float* SSA, const float* SSB, const float* FIN, const float* c_re, const float* c_im, const float* dvec, bf16_t* YG) {
;     ...
; #pragma unroll 4
;             for (int t16 = 0; t16 < 16; ++t16) { const f32x2 x = *(const f32x2*)(X + t16 * 132 + 2 * lane);
;                 const float nr = A[0] * sr - A[1] * si + x.x, ni = A[0] * si + A[1] * sr + x.y; sr = nr; si = ni;
;                 Sb[t16 * 68 + lane] = cvt_pk_bf16(sr, si); }
;             wave_lds_fence();
;             f32x4 y = {0.f, 0.f, 0.f, 0.f};
; #pragma unroll
;             for (int ks = 0; ks < 4; ++ks) { const u32x4 sw = *(const LAS u32x4*)(Sb + fr * 68 + 16 * ks + 4 * fq); const bf16x8 sf = __builtin_bit_cast(bf16x8, sw);
;                 y = mfma16(cf[ks], sf, y);
;                 asm volatile("" :: "v"(sf), "v"(cf[ks]), "v"(y)); }
;             const f32x4 u = {h2f(uh.x), h2f(uh.x >> 16), h2f(uh.y), h2f(uh.y >> 16)};
;             y += dv * u;
;             f32x4 o;
; #pragma unroll
;             for (int j = 0; j < 4; ++j) o[j] = gelu_tanh(y[j]);
;             *(u32x2*)(YG + (tok0 + fr) * 512 + g * 16 + 4 * fq) = pack4(o);
.LBB0_498:
	v_add_u32_e32 v49, 0, v3
	ds_read_b64 v[126:127], v49
	ds_read_b64 v[128:129], v49 offset:528
	ds_read_b64 v[130:131], v49 offset:1056
	ds_read_b64 v[132:133], v49 offset:1584
	v_add_u32_e32 v68, 0, v48
	s_add_i32 s6, s6, -4
	v_add_u32_e32 v48, 0x440, v48
	v_add_u32_e32 v3, 0x840, v3
	v_mul_f32_e32 v66, v37, v100
	v_fma_f32 v66, v36, v98, -v66
	v_mul_f32_e32 v50, v36, v100
	v_fmac_f32_e32 v50, v37, v98
	s_waitcnt lgkmcnt(3)
	v_add_f32_e32 v66, v66, v126
	v_add_f32_e32 v67, v50, v127
	v_cvt_pkrtz_f16_f32 v50, v66, v67
	v_add_u32_e32 v51, 0x10800, v68
	ds_write_b32 v51, v50
	v_mul_f32_e32 v69, v37, v67
	v_fma_f32 v69, v36, v66, -v69
	v_mul_f32_e32 v50, v36, v67
	v_fmac_f32_e32 v50, v37, v66
	s_waitcnt lgkmcnt(3)
	v_add_f32_e32 v69, v69, v128
	v_add_f32_e32 v66, v50, v129
	v_cvt_pkrtz_f16_f32 v50, v69, v66
	v_add_u32_e32 v51, 0x10910, v68
	ds_write_b32 v51, v50
	v_mul_f32_e32 v67, v37, v66
	v_fma_f32 v67, v36, v69, -v67
	v_mul_f32_e32 v50, v36, v66
	v_fmac_f32_e32 v50, v37, v69
	s_waitcnt lgkmcnt(3)
	v_add_f32_e32 v67, v67, v130
	v_add_f32_e32 v66, v50, v131
	v_cvt_pkrtz_f16_f32 v50, v67, v66
	v_add_u32_e32 v51, 0x10a20, v68
	ds_write_b32 v51, v50
	v_mul_f32_e32 v49, v37, v66
	v_fma_f32 v49, v36, v67, -v49
	v_mul_f32_e32 v50, v36, v66
	v_fmac_f32_e32 v50, v37, v67
	s_cmp_eq_u32 s6, 0
	s_waitcnt lgkmcnt(3)
	v_add_f32_e32 v98, v49, v132
	v_add_f32_e32 v100, v50, v133
	v_cvt_pkrtz_f16_f32 v49, v98, v100
	v_add_u32_e32 v50, 0x10b30, v68
	ds_write_b32 v50, v49
	s_cbranch_scc0 .LBB0_498
	s_waitcnt lgkmcnt(0)
	ds_read_b128 v[48:51], v111
	ds_read_b128 v[126:129], v111 offset:64
	ds_read_b128 v[130:133], v111 offset:128
	ds_read_b128 v[112:115], v111 offset:192
	s_add_i32 s18, s18, 1
	s_cmp_eq_u32 s18, 4
	s_waitcnt lgkmcnt(3)
	v_mfma_f32_16x16x32_f16 v[66:69], v[56:59], v[48:51], 0
	s_waitcnt lgkmcnt(2)
	v_mfma_f32_16x16x32_f16 v[66:69], v[52:55], v[126:129], v[66:69]
	s_waitcnt lgkmcnt(1)
	v_mfma_f32_16x16x32_f16 v[66:69], v[44:47], v[130:133], v[66:69]
	s_waitcnt lgkmcnt(0)
	v_mfma_f32_16x16x32_f16 v[48:51], v[38:41], v[112:115], v[66:69]
	s_waitcnt vmcnt(0)
	v_cvt_f32_f16 v3, v64
	v_lshrrev_b32_e32 v64, 16, v64
	s_nop 5
	v_fma_f32 v3, v72, v3, v48
	v_mul_f32_e32 v48, 0x3d372713, v3
	v_mul_f32_e32 v48, v3, v48
	v_fma_f32 v48, v3, v48, v3
	v_mul_f32_e32 v48, 0x3f4c422a, v48
	v_mul_f32_e32 v48, -2.0, v48
	v_mul_f32_e32 v48, 0x3fb8aa3b, v48
	v_exp_f32_e32 v48, v48
	v_cvt_f32_f16 v64, v64
	v_cvt_f32_f16 v66, v65
	v_lshrrev_b32_e32 v65, 16, v65
	v_add_f32_e32 v48, 1.0, v48
	v_rcp_f32_e32 v48, v48
	v_cvt_f32_f16 v65, v65
	s_nop 0
	v_fmac_f32_e32 v51, v75, v65
	v_mul_f32_e32 v3, v3, v48
	v_fma_f32 v48, v73, v64, v49
	v_mul_f32_e32 v49, 0x3d372713, v48
	v_mul_f32_e32 v49, v48, v49
	v_fma_f32 v49, v48, v49, v48
	v_mul_f32_e32 v49, 0x3f4c422a, v49
	v_mul_f32_e32 v49, -2.0, v49
	v_mul_f32_e32 v49, 0x3fb8aa3b, v49
	v_exp_f32_e32 v49, v49
	s_nop 0
	v_add_f32_e32 v49, 1.0, v49
	v_rcp_f32_e32 v49, v49
	s_nop 0
	v_mul_f32_e32 v48, v48, v49
	v_fma_f32 v49, v74, v66, v50
	v_mul_f32_e32 v50, 0x3d372713, v49
	v_mul_f32_e32 v50, v49, v50
	v_fma_f32 v50, v49, v50, v49
	v_mul_f32_e32 v50, 0x3f4c422a, v50
	v_mul_f32_e32 v50, -2.0, v50
	v_mul_f32_e32 v50, 0x3fb8aa3b, v50
	v_exp_f32_e32 v50, v50
	v_cvt_pkrtz_f16_f32 v48, v3, v48
	v_add_f32_e32 v50, 1.0, v50
	v_rcp_f32_e32 v50, v50
	s_nop 0
	v_mul_f32_e32 v49, v49, v50
	v_mul_f32_e32 v50, 0x3d372713, v51
	v_mul_f32_e32 v50, v51, v50
	v_fma_f32 v50, v51, v50, v51
	v_mul_f32_e32 v50, 0x3f4c422a, v50
	v_mul_f32_e32 v50, -2.0, v50
	v_mul_f32_e32 v50, 0x3fb8aa3b, v50
	v_exp_f32_e32 v50, v50
	s_nop 0
	v_add_f32_e32 v50, 1.0, v50
	v_rcp_f32_e32 v50, v50
	s_nop 0
	v_mul_f32_e32 v50, v51, v50
	v_cvt_pkrtz_f16_f32 v49, v49, v50
	v_lshl_add_u64 v[50:51], v[62:63], 1, v[60:61]
	global_store_dwordx2 v[50:51], v[48:49], off
	s_cbranch_scc0 .LBB0_495
	s_add_i32 s10, s10, s76
	s_cmpk_gt_i32 s10, 0x1ff
	s_cbranch_scc0 .LBB0_472
